# tile order: merged-branch and w_out GEMMs walk row panels 8 at a time (WGM 8) so each workgroup's consecutive tile pairs reuse the same A panel; on top of k-inner Gray MFMA order
# speedup vs baseline: 1.0008x; 1.0008x over previous
.LBB0_555:
	s_or_b64 exec, exec, s[0:1]
	v_readlane_b32 s0, v253, 2
	v_readlane_b32 s26, v253, 1
	s_mov_b32 s12, s65
	v_readlane_b32 s27, v253, 0
	v_readlane_b32 s1, v253, 3
	v_mov_b32_e32 v2, v0
	s_waitcnt lgkmcnt(0)
	s_barrier
	s_cmpk_gt_i32 s27, 0x5ff
	v_readfirstlane_b32 s10, v2
	s_cbranch_scc1 .LBB0_577
	v_bfe_i32 v4, v2, 27, 1
	v_lshlrev_b32_e32 v6, 4, v2
	v_lshrrev_b32_e32 v4, 22, v4
	v_add_u32_e32 v4, v6, v4
	v_and_b32_e32 v4, 0xfffffc00, v4
	v_sub_u32_e32 v4, v6, v4
	v_lshrrev_b32_e32 v5, 4, v4
	v_bitop3_b32 v5, v5, v4, 32 bitop3:0x6c
	v_ashrrev_i32_e32 v4, 31, v4
	v_lshrrev_b32_e32 v4, 26, v4
	v_ashrrev_i32_e32 v3, 31, v2
	v_add_u32_e32 v4, v5, v4
	v_lshrrev_b32_e32 v3, 26, v3
	v_ashrrev_i32_e32 v4, 6, v4
	v_add_u32_e32 v3, v2, v3
	v_mul_i32_i24_e32 v9, 64, v4
	v_ashrrev_i32_e32 v3, 6, v3
	v_sub_u32_e32 v5, v5, v9
	v_lshlrev_b32_e32 v7, 3, v3
	v_lshlrev_b32_e32 v8, 5, v3
	v_ashrrev_i16_sdwa v5, v1, sext(v5) dst_sel:DWORD dst_unused:UNUSED_PAD src0_sel:DWORD src1_sel:BYTE_0
	v_and_b32_e32 v7, -16, v7
	v_and_b32_e32 v8, 32, v8
	v_bfe_i32 v5, v5, 0, 16
	v_add_u32_e32 v7, v4, v7
	s_waitcnt vmcnt(0)
	v_and_b32_e32 v11, 3, v4
	s_mov_b32 s6, 0xfffe0
	v_add_lshl_u32 v8, v8, v5, 1
	v_lshlrev_b32_e32 v9, 1, v7
	v_lshrrev_b32_e32 v10, 2, v7
	v_and_or_b32 v11, v7, s6, v11
	v_lshl_add_u32 v196, v7, 12, v8
	v_add_u32_e32 v7, 0x2000, v6
	v_ashrrev_i32_e32 v6, 31, v7
	v_lshrrev_b32_e32 v6, 22, v6
	v_and_b32_e32 v9, 24, v9
	v_and_b32_e32 v10, 4, v10
	v_add_u32_e32 v6, v7, v6
	v_or3_b32 v9, v11, v10, v9
	v_ashrrev_i32_e32 v6, 10, v6
	s_load_dwordx2 s[4:5], s[0:1], 0x98
	v_lshl_add_u32 v197, v9, 12, v8
	v_mul_i32_i24_e32 v8, 0x400, v6
	v_sub_u32_e32 v7, v7, v8
	v_lshrrev_b32_e32 v8, 4, v7
	v_bitop3_b32 v8, v8, v7, 32 bitop3:0x6c
	v_lshlrev_b32_e32 v7, 3, v6
	v_and_b32_e32 v9, -16, v7
	v_ashrrev_i32_e32 v7, 31, v8
	s_waitcnt lgkmcnt(0)
	s_add_u32 s0, s4, 0x66800000
	v_lshrrev_b32_e32 v7, 26, v7
	s_addc_u32 s1, s5, 0
	v_add_u32_e32 v10, v8, v7
	s_add_u32 s2, s4, 0xb100000
	v_ashrrev_i32_e32 v7, 6, v10
	s_addc_u32 s3, s5, 0
	v_add_u32_e32 v9, v7, v9
	v_and_b32_e32 v13, 3, v7
	s_ashr_i32 s28, s27, 31
	v_and_or_b32 v13, v9, s6, v13
	s_lshr_b32 s6, s28, 29
	s_add_i32 s6, s27, s6
	s_ashr_i32 s11, s10, 6
	s_ashr_i32 s7, s6, 3
	s_and_b32 s6, s6, -8
	s_ashr_i32 s13, s10, 8
	s_lshl_b32 s15, s11, 10
	s_sub_i32 s6, s27, s6
	s_cmp_lt_i32 s6, 0
	s_movk_i32 s8, 0xc1
	s_cselect_b32 s8, s8, 0xc0
	s_mul_i32 s6, s6, s8
	s_add_i32 s6, s6, s7
	s_mov_b32 s100, s6
	s_ashr_i32 s7, s6, 31
	s_lshr_b32 s7, s7, 27
	s_add_i32 s7, s6, s7
	s_ashr_i32 s8, s7, 5
	s_and_b32 s7, s7, 0xffe0
	s_sub_i32 s6, s6, s7
	s_bfe_i32 s7, s6, 0x80000
	s_bfe_u32 s7, s7, 0x2000d
	v_and_b32_e32 v10, 0xc0, v10
	s_add_i32 s7, s6, s7
	v_sub_u32_e32 v8, v8, v10
	s_bfe_i32 s9, s7, 0x80000
	v_lshlrev_b32_e32 v11, 5, v6
	v_ashrrev_i16_sdwa v8, v1, sext(v8) dst_sel:DWORD dst_unused:UNUSED_PAD src0_sel:DWORD src1_sel:BYTE_0
	v_lshlrev_b32_e32 v10, 1, v9
	v_lshrrev_b32_e32 v12, 2, v9
	s_sext_i32_i16 s9, s9
	v_and_b32_e32 v11, 32, v11
	v_bfe_i32 v8, v8, 0, 16
	v_and_b32_e32 v10, 24, v10
	v_and_b32_e32 v12, 4, v12
	s_and_b32 s7, s7, 0xfc
	s_bfe_u32 s14, s100, 0x30003
	s_add_i32 s29, s12, 0x10000
	v_or3_b32 v10, v13, v12, v10
	v_add_lshl_u32 v11, v11, v8, 1
	s_sub_i32 s6, s6, s7
	s_lshl_b32 s22, s14, 20
	s_add_i32 s30, s29, s15
	v_lshl_add_u32 v198, v9, 12, v11
	v_lshl_add_u32 v199, v10, 12, v11
	s_lshl_b32 s8, s8, 2
	s_sext_i32_i8 s6, s6
	v_add_u32_e32 v9, s22, v197
	s_mov_b32 m0, s30
	s_add_i32 s31, s30, 0x2000
	s_add_i32 s34, s12, 0x14000
	s_and_b32 s101, s100, 7
	s_lshr_b32 s16, s100, 6
	s_lshl_b32 s16, s16, 3
	s_add_i32 s16, s16, s101
	global_load_lds_dwordx4 v9, s[2:3]
	v_add_u32_e32 v9, s22, v199
	s_mov_b32 m0, s31
	s_or_b32 s6, s22, 0x80000
	s_add_i32 s35, s34, s15
	global_load_lds_dwordx4 v9, s[2:3]
	v_add_u32_e32 v9, s6, v197
	s_mov_b32 m0, s35
	s_add_i32 s36, s35, 0x2000
	global_load_lds_dwordx4 v9, s[2:3]
	v_add_u32_e32 v9, s6, v199
	s_mov_b32 m0, s36
	s_lshl_b32 s59, s16, 20
	s_add_i32 s37, s12, s15
	global_load_lds_dwordx4 v9, s[2:3]
	v_add_u32_e32 v9, s59, v196
	s_mov_b32 m0, s37
	s_add_i32 s38, s37, 0x2000
	global_load_lds_dwordx4 v9, s[0:1]
	v_add_u32_e32 v9, s59, v198
	s_mov_b32 m0, s38
	s_or_b32 s6, s59, 0x80000
	s_add_i32 s39, s37, 0x4000
	global_load_lds_dwordx4 v9, s[0:1]
	v_add_u32_e32 v9, s6, v196
	s_mov_b32 m0, s39
	s_add_i32 s40, s37, 0x6000
	global_load_lds_dwordx4 v9, s[0:1]
	v_add_u32_e32 v9, s6, v198
	s_mov_b32 m0, s40
	s_cmp_eq_u32 s13, 1
	global_load_lds_dwordx4 v9, s[0:1]
	s_cselect_b64 s[6:7], -1, 0
	s_cmp_lg_u32 s13, 1
	s_cbranch_scc1 .LBB0_558
	s_barrier

.LBB0_561:
	s_add_i32 s54, s54, 1
	s_mul_i32 s4, s54, s51
	s_mul_hi_u32 s5, s54, s26
	s_add_i32 s5, s5, s4
	s_mul_i32 s4, s54, s26
	s_add_u32 s18, s4, s27
	s_addc_u32 s19, s5, s28
	v_cmp_gt_i64_e32 vcc, s[18:19], v[208:209]
	v_cmp_lt_i64_e64 s[4:5], s[18:19], v[210:211]
	s_cbranch_vccnz .LBB0_563
	s_ashr_i32 s15, s18, 31
	s_lshr_b32 s15, s15, 29
	s_add_i32 s15, s18, s15
	s_ashr_i32 s17, s15, 3
	s_and_b32 s15, s15, -8
	s_sub_i32 s15, s18, s15
	s_cmp_lt_i32 s15, 0
	s_movk_i32 s18, 0xc1
	s_cselect_b32 s18, s18, 0xc0
	s_mul_i32 s15, s15, s18
	s_add_i32 s15, s15, s17
	s_ashr_i32 s17, s15, 31
	s_lshr_b32 s17, s17, 26
	s_add_i32 s17, s15, s17
	s_ashr_i32 s18, s17, 6
	s_lshl_b32 s18, s18, 3
	s_sub_i32 s19, 0xc0, s18
	s_min_i32 s19, s19, 8
	s_abs_i32 s20, s19
	v_cvt_f32_u32_e32 v2, s20
	s_sub_i32 s23, 0, s20
	s_andn2_b32 s17, s17, 63
	s_sub_i32 s15, s15, s17
	v_rcp_iflag_f32_e32 v2, v2
	s_abs_i32 s17, s15
	s_xor_b32 s21, s15, s19
	s_ashr_i32 s21, s21, 31
	v_mul_f32_e32 v2, 0x4f7ffffe, v2
	v_cvt_u32_f32_e32 v2, v2
	s_nop 0
	v_readfirstlane_b32 s24, v2
	s_mul_i32 s23, s23, s24
	s_mul_hi_u32 s23, s24, s23
	s_add_i32 s24, s24, s23
	s_mul_hi_u32 s23, s17, s24
	s_mul_i32 s24, s23, s20
	s_sub_i32 s17, s17, s24
	s_add_i32 s25, s23, 1
	s_sub_i32 s24, s17, s20
	s_cmp_ge_u32 s17, s20
	s_cselect_b32 s23, s25, s23
	s_cselect_b32 s17, s24, s17
	s_add_i32 s24, s23, 1
	s_cmp_ge_u32 s17, s20
	s_cselect_b32 s17, s24, s23
	s_xor_b32 s17, s17, s21
	s_sub_i32 s55, s17, s21
	s_mul_i32 s17, s55, s19
	s_sub_i32 s15, s15, s17
	s_add_i32 s56, s18, s15

.LBB0_607:
	s_or_b64 exec, exec, s[0:1]
	v_readlane_b32 s0, v253, 2
	v_readlane_b32 s14, v253, 0
	s_mov_b32 s12, s65
	v_readlane_b32 s15, v253, 1
	v_readlane_b32 s1, v253, 3
	v_mov_b32_e32 v3, v0
	s_waitcnt lgkmcnt(0)
	s_barrier
	s_cmpk_gt_i32 s14, 0x5ff
	v_readfirstlane_b32 s10, v3
	s_cbranch_scc1 .LBB0_623
	v_bfe_i32 v4, v3, 27, 1
	v_lshlrev_b32_e32 v6, 4, v3
	v_lshrrev_b32_e32 v4, 22, v4
	v_add_u32_e32 v4, v6, v4
	v_and_b32_e32 v4, 0xfffffc00, v4
	v_sub_u32_e32 v4, v6, v4
	v_lshrrev_b32_e32 v5, 4, v4
	v_bitop3_b32 v5, v5, v4, 32 bitop3:0x6c
	v_ashrrev_i32_e32 v4, 31, v4
	v_lshrrev_b32_e32 v4, 26, v4
	v_ashrrev_i32_e32 v2, 31, v3
	v_add_u32_e32 v4, v5, v4
	v_lshrrev_b32_e32 v2, 26, v2
	v_ashrrev_i32_e32 v4, 6, v4
	v_add_u32_e32 v2, v3, v2
	v_mul_i32_i24_e32 v9, 64, v4
	v_ashrrev_i32_e32 v2, 6, v2
	v_sub_u32_e32 v5, v5, v9
	v_lshlrev_b32_e32 v7, 3, v2
	v_lshlrev_b32_e32 v8, 5, v2
	v_ashrrev_i16_sdwa v5, v1, sext(v5) dst_sel:DWORD dst_unused:UNUSED_PAD src0_sel:DWORD src1_sel:BYTE_0
	v_and_b32_e32 v7, -16, v7
	v_and_b32_e32 v8, 32, v8
	v_bfe_i32 v5, v5, 0, 16
	v_add_u32_e32 v7, v4, v7
	s_waitcnt vmcnt(0)
	v_and_b32_e32 v11, 3, v4
	s_mov_b32 s6, 0xfffe0
	v_add_lshl_u32 v8, v8, v5, 1
	v_lshlrev_b32_e32 v9, 1, v7
	v_lshrrev_b32_e32 v10, 2, v7
	v_and_or_b32 v11, v7, s6, v11
	v_lshl_add_u32 v132, v7, 12, v8
	v_add_u32_e32 v7, 0x2000, v6
	v_ashrrev_i32_e32 v6, 31, v7
	v_lshrrev_b32_e32 v6, 22, v6
	v_and_b32_e32 v9, 24, v9
	v_and_b32_e32 v10, 4, v10
	v_add_u32_e32 v6, v7, v6
	v_or3_b32 v9, v11, v10, v9
	v_ashrrev_i32_e32 v6, 10, v6
	s_load_dwordx2 s[4:5], s[0:1], 0x98
	v_lshl_add_u32 v133, v9, 12, v8
	v_mul_i32_i24_e32 v8, 0x400, v6
	v_sub_u32_e32 v7, v7, v8
	v_lshrrev_b32_e32 v8, 4, v7
	v_bitop3_b32 v8, v8, v7, 32 bitop3:0x6c
	v_lshlrev_b32_e32 v7, 3, v6
	v_and_b32_e32 v9, -16, v7
	v_ashrrev_i32_e32 v7, 31, v8
	s_waitcnt lgkmcnt(0)
	s_add_u32 s0, s4, 0x5a700000
	v_lshrrev_b32_e32 v7, 26, v7
	s_addc_u32 s1, s5, 0
	v_add_u32_e32 v10, v8, v7
	s_add_u32 s2, s4, 0xb900000
	v_ashrrev_i32_e32 v7, 6, v10
	s_addc_u32 s3, s5, 0
	v_add_u32_e32 v9, v7, v9
	v_and_b32_e32 v13, 3, v7
	s_ashr_i32 s16, s14, 31
	v_and_or_b32 v13, v9, s6, v13
	s_lshr_b32 s6, s16, 29
	s_add_i32 s6, s14, s6
	s_ashr_i32 s11, s10, 6
	s_ashr_i32 s7, s6, 3
	s_and_b32 s6, s6, -8
	s_ashr_i32 s13, s10, 8
	s_lshl_b32 s35, s11, 10
	s_sub_i32 s6, s14, s6
	s_cmp_lt_i32 s6, 0
	s_movk_i32 s8, 0xc1
	s_cselect_b32 s8, s8, 0xc0
	s_mul_i32 s6, s6, s8
	s_add_i32 s6, s6, s7
	s_mov_b32 s100, s6
	s_ashr_i32 s7, s6, 31
	s_lshr_b32 s7, s7, 27
	s_add_i32 s7, s6, s7
	s_ashr_i32 s8, s7, 5
	s_and_b32 s7, s7, 0xffe0
	s_sub_i32 s6, s6, s7
	s_bfe_i32 s7, s6, 0x80000
	s_bfe_u32 s7, s7, 0x2000d
	v_and_b32_e32 v10, 0xc0, v10
	s_add_i32 s7, s6, s7
	v_sub_u32_e32 v8, v8, v10
	s_bfe_i32 s9, s7, 0x80000
	v_lshlrev_b32_e32 v11, 5, v6
	v_ashrrev_i16_sdwa v8, v1, sext(v8) dst_sel:DWORD dst_unused:UNUSED_PAD src0_sel:DWORD src1_sel:BYTE_0
	v_lshlrev_b32_e32 v10, 1, v9
	v_lshrrev_b32_e32 v12, 2, v9
	s_sext_i32_i16 s9, s9
	v_and_b32_e32 v11, 32, v11
	v_bfe_i32 v8, v8, 0, 16
	v_and_b32_e32 v10, 24, v10
	v_and_b32_e32 v12, 4, v12
	s_and_b32 s7, s7, 0xfc
	s_bfe_u32 s41, s100, 0x30003
	s_add_i32 s17, s12, 0x10000
	v_or3_b32 v10, v13, v12, v10
	v_add_lshl_u32 v11, v11, v8, 1
	s_sub_i32 s6, s6, s7
	s_lshl_b32 s45, s41, 20
	s_add_i32 s18, s17, s35
	v_lshl_add_u32 v134, v9, 12, v11
	v_lshl_add_u32 v135, v10, 12, v11
	s_lshl_b32 s8, s8, 2
	s_sext_i32_i8 s6, s6
	v_add_u32_e32 v9, s45, v133
	s_mov_b32 m0, s18
	s_add_i32 s19, s18, 0x2000
	s_add_i32 s20, s12, 0x14000
	s_and_b32 s101, s100, 7
	s_lshr_b32 s42, s100, 6
	s_lshl_b32 s42, s42, 3
	s_add_i32 s42, s42, s101
	s_sub_i32 s42, 0xbf, s42
	global_load_lds_dwordx4 v9, s[2:3]
	v_add_u32_e32 v9, s45, v135
	s_mov_b32 m0, s19
	s_or_b32 s6, s45, 0x80000
	s_add_i32 s21, s20, s35
	global_load_lds_dwordx4 v9, s[2:3]
	v_add_u32_e32 v9, s6, v133
	s_mov_b32 m0, s21
	s_add_i32 s22, s21, 0x2000
	global_load_lds_dwordx4 v9, s[2:3]
	v_add_u32_e32 v9, s6, v135
	s_mov_b32 m0, s22
	s_lshl_b32 s46, s42, 20
	s_add_i32 s23, s12, s35
	global_load_lds_dwordx4 v9, s[2:3]
	v_add_u32_e32 v9, s46, v132
	s_mov_b32 m0, s23
	s_add_i32 s24, s23, 0x2000
	global_load_lds_dwordx4 v9, s[0:1]
	v_add_u32_e32 v9, s46, v134
	s_mov_b32 m0, s24
	s_or_b32 s6, s46, 0x80000
	s_add_i32 s25, s23, 0x4000
	global_load_lds_dwordx4 v9, s[0:1]
	v_add_u32_e32 v9, s6, v132
	s_mov_b32 m0, s25
	s_add_i32 s26, s23, 0x6000
	global_load_lds_dwordx4 v9, s[0:1]
	v_add_u32_e32 v9, s6, v134
	s_mov_b32 m0, s26
	s_cmp_eq_u32 s13, 1
	global_load_lds_dwordx4 v9, s[0:1]
	s_cselect_b64 s[6:7], -1, 0
	s_cmp_lg_u32 s13, 1
	s_cbranch_scc1 .LBB0_610
	s_barrier

.LBB0_613:
	s_add_i32 s38, s38, 1
	s_mul_i32 s4, s38, s37
	s_mul_hi_u32 s5, s38, s15
	s_add_i32 s5, s5, s4
	s_mul_i32 s4, s38, s15
	s_add_u32 s12, s4, s14
	s_addc_u32 s13, s5, s16
	v_cmp_gt_i64_e32 vcc, s[12:13], v[208:209]
	v_cmp_lt_i64_e64 s[4:5], s[12:13], v[210:211]
	s_cbranch_vccnz .LBB0_615
	s_ashr_i32 s13, s12, 31
	s_lshr_b32 s13, s13, 29
	s_add_i32 s13, s12, s13
	s_ashr_i32 s39, s13, 3
	s_and_b32 s13, s13, -8
	s_sub_i32 s12, s12, s13
	s_cmp_lt_i32 s12, 0
	s_movk_i32 s13, 0xc1
	s_cselect_b32 s13, s13, 0xc0
	s_mul_i32 s12, s12, s13
	s_add_i32 s12, s12, s39
	s_ashr_i32 s13, s12, 31
	s_lshr_b32 s13, s13, 26
	s_add_i32 s13, s12, s13
	s_ashr_i32 s39, s13, 6
	s_lshl_b32 s40, s39, 3
	s_sub_i32 s39, 0xc0, s40
	s_min_i32 s43, s39, 8
	s_abs_i32 s39, s43
	v_cvt_f32_u32_e32 v2, s39
	s_sub_i32 s47, 0, s39
	s_andn2_b32 s13, s13, 63
	s_sub_i32 s12, s12, s13
	v_rcp_iflag_f32_e32 v2, v2
	s_abs_i32 s13, s12
	s_xor_b32 s44, s12, s43
	s_ashr_i32 s44, s44, 31
	v_mul_f32_e32 v2, 0x4f7ffffe, v2
	v_cvt_u32_f32_e32 v2, v2
	s_nop 0
	v_readfirstlane_b32 s48, v2
	s_mul_i32 s47, s47, s48
	s_mul_hi_u32 s47, s48, s47
	s_add_i32 s48, s48, s47
	s_mul_hi_u32 s47, s13, s48
	s_mul_i32 s48, s47, s39
	s_sub_i32 s13, s13, s48
	s_add_i32 s49, s47, 1
	s_sub_i32 s48, s13, s39
	s_cmp_ge_u32 s13, s39
	s_cselect_b32 s47, s49, s47
	s_cselect_b32 s13, s48, s13
	s_add_i32 s48, s47, 1
	s_cmp_ge_u32 s13, s39
	s_cselect_b32 s13, s48, s47
	s_xor_b32 s13, s13, s44
	s_sub_i32 s39, s13, s44
	s_mul_i32 s13, s39, s43
	s_sub_i32 s12, s12, s13
	s_add_i32 s40, s40, s12
	s_sub_i32 s40, 0xbf, s40
